# phase B: no store drain at prompt-unit end barriers and spatial-unit tops (stores stay in flight across the LDS-only barrier)
# baseline (speedup 1.0000x reference)
.Lattn_wide_done_a:
	s_waitcnt lgkmcnt(0)
	s_waitcnt lgkmcnt(0)
	s_barrier

.LBB0_873:
	s_ashr_i32 s2, s10, 2
	s_lshl_b32 s8, s10, 7
	s_ashr_i32 s3, s2, 31
	s_and_b32 s12, s8, 0x180
	v_mov_b32_e32 v1, v0
	s_lshl_b64 s[2:3], s[2:3], 7
	s_lshl_b32 s11, s12, 2
	s_add_u32 s8, s55, s11
	v_lshlrev_b32_e32 v74, 3, v1
	v_and_b32_e32 v10, 0x78, v74
	s_addc_u32 s9, s56, 0
	s_nop 0
	v_lshlrev_b32_e32 v6, 2, v10
	global_load_dwordx4 v[2:5], v6, s[8:9] offset:16
	s_nop 0
	global_load_dwordx4 v[6:9], v6, s[8:9]
	s_lshl_b32 s18, s12, 1
	s_add_u32 s8, s17, s18
	v_ashrrev_i32_e32 v72, 4, v1
	s_addc_u32 s9, s28, 0
	v_lshlrev_b32_e32 v14, 1, v10
	v_lshl_add_u64 v[60:61], s[8:9], 0, v[14:15]
	v_cmp_gt_i32_e64 s[42:43], s72, v72
	v_mov_b32_e32 v16, 0
	v_mov_b32_e32 v24, 1.0
	v_mov_b32_e32 v48, 1.0
	v_mov_b32_e32 v49, 1.0
	v_mov_b32_e32 v50, 1.0
	v_mov_b32_e32 v51, 1.0
	v_mov_b32_e32 v56, 1.0
	v_mov_b32_e32 v57, 1.0
	v_mov_b32_e32 v58, 1.0
	v_mov_b32_e32 v59, 1.0
	v_mov_b32_e32 v32, 0
	v_mov_b32_e32 v33, 0
	v_mov_b32_e32 v34, 0
	v_mov_b32_e32 v35, 0
	s_and_saveexec_b64 s[8:9], s[42:43]
	s_cbranch_execz .LBB0_875
	v_ashrrev_i32_e32 v73, 31, v72
	v_lshl_add_u64 v[10:11], s[2:3], 0, v[72:73]
	v_lshlrev_b64 v[12:13], 10, v[10:11]
	v_lshlrev_b64 v[10:11], 5, v[10:11]
	v_lshl_add_u64 v[10:11], s[6:7], 0, v[10:11]
	v_lshl_add_u64 v[12:13], v[60:61], 0, v[12:13]
	global_load_dwordx4 v[48:51], v[10:11], off offset:16
	global_load_dwordx4 v[32:35], v[12:13], off
	global_load_dwordx4 v[56:59], v[10:11], off

.LBB0_1030:
	s_ashr_i32 s0, s10, 2
	s_ashr_i32 s1, s0, 31
	s_lshl_b64 s[2:3], s[0:1], 7
	s_lshl_b32 s0, s10, 7
	s_and_b32 s8, s0, 0x180
	v_mov_b32_e32 v1, v0
	s_lshl_b32 s11, s8, 2
	s_add_u32 s0, s55, s11
	v_lshlrev_b32_e32 v74, 3, v1
	v_and_b32_e32 v10, 0x78, v74
	s_addc_u32 s1, s56, 0
	s_nop 0
	v_lshlrev_b32_e32 v6, 2, v10
	global_load_dwordx4 v[2:5], v6, s[0:1] offset:16
	s_nop 0
	global_load_dwordx4 v[6:9], v6, s[0:1]
	s_lshl_b32 s18, s8, 1
	s_add_u32 s0, s17, s18
	v_ashrrev_i32_e32 v72, 4, v1
	s_addc_u32 s1, s20, 0
	v_lshlrev_b32_e32 v14, 1, v10
	v_lshl_add_u64 v[60:61], s[0:1], 0, v[14:15]
	v_cmp_gt_i32_e64 s[40:41], s72, v72
	s_waitcnt vmcnt(2)
	v_mov_b32_e32 v16, 0
	v_mov_b32_e32 v24, 1.0
	v_mov_b32_e32 v48, 1.0
	v_mov_b32_e32 v49, 1.0
	v_mov_b32_e32 v50, 1.0
	v_mov_b32_e32 v51, 1.0
	v_mov_b32_e32 v56, 1.0
	v_mov_b32_e32 v57, 1.0
	v_mov_b32_e32 v58, 1.0
	v_mov_b32_e32 v59, 1.0
	v_mov_b32_e32 v32, 0
	v_mov_b32_e32 v33, 0
	v_mov_b32_e32 v34, 0
	v_mov_b32_e32 v35, 0
	s_and_saveexec_b64 s[0:1], s[40:41]
	s_cbranch_execz .LBB0_1032
	v_ashrrev_i32_e32 v73, 31, v72
	v_lshl_add_u64 v[10:11], s[2:3], 0, v[72:73]
	v_lshlrev_b64 v[12:13], 10, v[10:11]
	v_lshlrev_b64 v[10:11], 5, v[10:11]
	v_lshl_add_u64 v[10:11], s[6:7], 0, v[10:11]
	v_lshl_add_u64 v[12:13], v[60:61], 0, v[12:13]
	global_load_dwordx4 v[48:51], v[10:11], off offset:16
	global_load_dwordx4 v[32:35], v[12:13], off
	global_load_dwordx4 v[56:59], v[10:11], off

.LBB0_1196:
	s_ashr_i32 s0, s10, 2
	s_ashr_i32 s1, s0, 31
	s_lshl_b64 s[2:3], s[0:1], 7
	s_lshl_b32 s0, s10, 7
	s_and_b32 s8, s0, 0x180
	v_mov_b32_e32 v1, v0
	s_lshl_b32 s11, s8, 2
	s_add_u32 s0, s55, s11
	v_lshlrev_b32_e32 v74, 3, v1
	v_and_b32_e32 v10, 0x78, v74
	s_addc_u32 s1, s56, 0
	s_nop 0
	v_lshlrev_b32_e32 v6, 2, v10
	global_load_dwordx4 v[2:5], v6, s[0:1] offset:16
	s_nop 0
	global_load_dwordx4 v[6:9], v6, s[0:1]
	s_lshl_b32 s18, s8, 1
	s_add_u32 s0, s17, s18
	v_ashrrev_i32_e32 v72, 4, v1
	s_addc_u32 s1, s20, 0
	v_lshlrev_b32_e32 v14, 1, v10
	v_lshl_add_u64 v[60:61], s[0:1], 0, v[14:15]
	v_cmp_gt_i32_e64 s[40:41], s72, v72
	v_mov_b32_e32 v16, 0
	v_mov_b32_e32 v24, 1.0
	v_mov_b32_e32 v48, 1.0
	v_mov_b32_e32 v49, 1.0
	v_mov_b32_e32 v50, 1.0
	v_mov_b32_e32 v51, 1.0
	v_mov_b32_e32 v56, 1.0
	v_mov_b32_e32 v57, 1.0
	v_mov_b32_e32 v58, 1.0
	v_mov_b32_e32 v59, 1.0
	v_mov_b32_e32 v32, 0
	v_mov_b32_e32 v33, 0
	v_mov_b32_e32 v34, 0
	v_mov_b32_e32 v35, 0
	s_and_saveexec_b64 s[0:1], s[40:41]
	s_cbranch_execz .LBB0_1198
	v_ashrrev_i32_e32 v73, 31, v72
	v_lshl_add_u64 v[10:11], s[2:3], 0, v[72:73]
	v_lshlrev_b64 v[12:13], 10, v[10:11]
	v_lshlrev_b64 v[10:11], 5, v[10:11]
	v_lshl_add_u64 v[10:11], s[6:7], 0, v[10:11]
	v_lshl_add_u64 v[12:13], v[60:61], 0, v[12:13]
	global_load_dwordx4 v[48:51], v[10:11], off offset:16
	global_load_dwordx4 v[32:35], v[12:13], off
	global_load_dwordx4 v[56:59], v[10:11], off
